# combo15 + indexer chunk loop: waves 0-3 read the next chunk's key fragments right after their EPI and start the next interval with the MFMAs (DMA wait one chunk further)
# speedup vs baseline: 1.0195x; 1.0105x over previous
.Lidxt1_join:
	ds_write_b32 v235, v192
	s_add_u32 s0, s90, 0x4000
	s_cmp_eq_u32 s94, s0
	s_cbranch_scc1 .Lidx_ypre_skip
	s_and_b32 s0, s0, 0xc000
	v_add_u32_e32 v237, s0, v225
	v_add_u32_e32 v236, v237, v226
	v_add_u32_e32 v239, v237, v228
	v_add_u32_e32 v238, v237, v227
	ds_read_b128 v[204:207], v236
	ds_read_b128 v[196:199], v238
	v_add_u32_e32 v240, v237, v229
	ds_read_b128 v[200:203], v239
	v_add_u32_e32 v36, v237, v230
	v_add_u32_e32 v37, v237, v231
	v_add_u32_e32 v38, v237, v232
	v_add_u32_e32 v39, v237, v233
	ds_read_b128 v[32:35], v236 offset:8192
	ds_read_b128 v[64:67], v238 offset:8192
	ds_read_b128 v[68:71], v239 offset:8192
	ds_read_b128 v[72:75], v240 offset:8192
	ds_read_b128 v[192:195], v240
	ds_read_b128 v[236:239], v36
	ds_read_b128 v[76:79], v36 offset:8192
	ds_read_b128 v[240:243], v37
	ds_read_b128 v[80:83], v37 offset:8192
	ds_read_b128 v[244:247], v38
	ds_read_b128 v[84:87], v38 offset:8192
	ds_read_b128 v[248:251], v39
	ds_read_b128 v[88:91], v39 offset:8192
	s_mov_b32 s32, 1
.Lidx_ypre_skip:
.LBB0_1164:
	s_add_i32 s96, s96, 1
	s_add_u32 s90, s90, 0x4000
	s_addc_u32 s91, s91, 0
	s_add_i32 s97, s97, -1
	s_cmp_eq_u32 s94, s90
	v_add_u32_e32 v235, 0x100, v235
	s_cbranch_scc1 .LBB0_1179

.LBB0_1168:
	s_andn2_b64 vcc, exec, s[0:1]
	s_cbranch_vccnz .LBB0_1170
	s_waitcnt vmcnt(0)
.LBB0_1170:
	s_mov_b64 s[0:1], 0
.LBB0_1171:
	s_andn2_b64 vcc, exec, s[0:1]
	s_cbranch_vccnz .LBB0_1173
	s_waitcnt vmcnt(2)
.LBB0_1173:
	s_barrier
	s_add_i32 s0, s96, 3
	s_cmp_gt_u32 s0, s93
	s_cbranch_scc1 .LBB0_1175
	s_cmp_lg_u32 s32, 0
	s_cbranch_scc1 .Lidx_dma_y
	s_add_i32 s0, s90, 0xc000
	s_and_b32 s0, s0, 0xc000
	s_add_i32 s0, s39, s0
	v_lshl_add_u64 v[192:193], v[220:221], 0, s[90:91]
	s_mov_b32 m0, s0
	s_nop 0
	global_load_lds_dwordx4 v[192:193], off
	v_lshl_add_u64 v[192:193], v[218:219], 0, s[90:91]
	s_add_i32 m0, s0, 0x400
	s_nop 0
	global_load_lds_dwordx4 v[192:193], off
	s_branch .LBB0_1175
.Lidx_dma_y:
	s_add_i32 s0, s90, 0xc000
	s_and_b32 s0, s0, 0xc000
	s_add_i32 s0, s39, s0
	v_lshl_add_u64 v[40:41], v[220:221], 0, s[90:91]
	s_mov_b32 m0, s0
	s_nop 0
	global_load_lds_dwordx4 v[40:41], off
	v_lshl_add_u64 v[40:41], v[218:219], 0, s[90:91]
	s_add_i32 m0, s0, 0x400
	s_nop 0
	global_load_lds_dwordx4 v[40:41], off
.LBB0_1175:
	s_cmp_lg_u32 s32, 0
	s_cbranch_scc1 .Lidx_y_stub
	s_and_b32 s0, s90, 0xc000
	v_add_u32_e32 v237, s0, v225
	v_add_u32_e32 v236, v237, v226
	v_add_u32_e32 v239, v237, v228
	v_add_u32_e32 v238, v237, v227
	ds_read_b128 v[204:207], v236
	ds_read_b128 v[196:199], v238
	v_add_u32_e32 v240, v237, v229
	ds_read_b128 v[200:203], v239
	ds_read_b128 v[192:195], v240
	s_cmp_gt_i32 s92, -1
	s_cselect_b64 s[0:1], -1, 0
	s_and_b64 s[0:1], s[84:85], s[0:1]
	s_andn2_b64 vcc, exec, s[0:1]
	s_cbranch_vccnz .LBB0_1177
	v_max_f32 v80, 0, v80
	v_max_f32 v48, 0, v48
	v_max_f32 v81, 0, v81
	v_max_f32 v49, 0, v49
	v_max_f32 v82, 0, v82
	v_max_f32 v50, 0, v50
	s_nop 0
	v_fma_f32 v80, v124, v80, 0
	v_fma_f32 v48, v124, v48, 0
	v_fmac_f32_e32 v80, v125, v81
	v_fmac_f32_e32 v48, v125, v49
	v_fmac_f32_e32 v80, v126, v82
	v_fmac_f32_e32 v48, v126, v50
	v_max_f32 v83, 0, v83
	v_max_f32 v51, 0, v51
	v_max_f32 v84, 0, v84
	v_max_f32 v52, 0, v52
	v_max_f32 v85, 0, v85
	v_max_f32 v53, 0, v53
	s_nop 0
	v_fmac_f32_e32 v80, v127, v83
	v_fmac_f32_e32 v48, v127, v51
	v_fmac_f32_e32 v80, v116, v84
	v_fmac_f32_e32 v48, v116, v52
	v_fmac_f32_e32 v80, v117, v85
	v_fmac_f32_e32 v48, v117, v53
	v_max_f32 v86, 0, v86
	v_max_f32 v54, 0, v54
	v_max_f32 v87, 0, v87
	v_max_f32 v55, 0, v55
	v_max_f32 v88, 0, v88
	v_max_f32 v56, 0, v56
	s_nop 0
	v_fmac_f32_e32 v80, v118, v86
	v_fmac_f32_e32 v48, v118, v54
	v_fmac_f32_e32 v80, v119, v87
	v_fmac_f32_e32 v48, v119, v55
	v_fmac_f32_e32 v80, v108, v88
	v_fmac_f32_e32 v48, v108, v56
	v_max_f32 v89, 0, v89
	v_max_f32 v57, 0, v57
	v_max_f32 v90, 0, v90
	v_max_f32 v58, 0, v58
	v_max_f32 v91, 0, v91
	v_max_f32 v59, 0, v59
	s_nop 0
	v_fmac_f32_e32 v80, v109, v89
	v_fmac_f32_e32 v48, v109, v57
	v_fmac_f32_e32 v80, v110, v90
	v_fmac_f32_e32 v48, v110, v58
	v_fmac_f32_e32 v80, v111, v91
	v_fmac_f32_e32 v48, v111, v59
	v_max_f32 v92, 0, v92
	v_max_f32 v60, 0, v60
	v_max_f32 v93, 0, v93
	v_max_f32 v61, 0, v61
	v_max_f32 v94, 0, v94
	v_max_f32 v62, 0, v62
	s_nop 0
	v_fmac_f32_e32 v80, v100, v92
	v_fmac_f32_e32 v48, v100, v60
	v_fmac_f32_e32 v80, v101, v93
	v_fmac_f32_e32 v48, v101, v61
	v_fmac_f32_e32 v80, v102, v94
	v_fmac_f32_e32 v48, v102, v62
	v_max_f32 v95, 0, v95
	v_max_f32 v63, 0, v63
	v_max_f32 v32, 0, v32
	v_lshl_add_u32 v49, s92, 8, v224
	v_fmac_f32_e32 v80, v103, v95
	v_fmac_f32_e32 v48, v103, v63
	s_nop 1
	v_permlane32_swap_b32_e32 v80, v48
	v_add_f32_e32 v48, v80, v48
	v_max_f32 v64, 0, v64
	ds_write_b32 v49, v48
	v_fma_f32 v48, v120, v64, 0
	v_fma_f32 v32, v120, v32, 0
	v_max_f32 v65, 0, v65
	v_max_f32 v33, 0, v33
	v_max_f32 v66, 0, v66
	v_max_f32 v34, 0, v34
	v_max_f32 v67, 0, v67
	v_max_f32 v35, 0, v35
	s_nop 0
	v_fmac_f32_e32 v48, v121, v65
	v_fmac_f32_e32 v32, v121, v33
	v_fmac_f32_e32 v48, v122, v66
	v_fmac_f32_e32 v32, v122, v34
	v_fmac_f32_e32 v48, v123, v67
	v_fmac_f32_e32 v32, v123, v35
	v_max_f32 v68, 0, v68
	v_max_f32 v36, 0, v36
	v_max_f32 v69, 0, v69
	v_max_f32 v37, 0, v37
	v_max_f32 v70, 0, v70
	v_max_f32 v38, 0, v38
	s_nop 0
	v_fmac_f32_e32 v48, v112, v68
	v_fmac_f32_e32 v32, v112, v36
	v_fmac_f32_e32 v48, v113, v69
	v_fmac_f32_e32 v32, v113, v37
	v_fmac_f32_e32 v48, v114, v70
	v_fmac_f32_e32 v32, v114, v38
	v_max_f32 v71, 0, v71
	v_max_f32 v39, 0, v39
	v_max_f32 v72, 0, v72
	v_max_f32 v40, 0, v40
	v_max_f32 v73, 0, v73
	v_max_f32 v41, 0, v41
	s_nop 0
	v_fmac_f32_e32 v48, v115, v71
	v_fmac_f32_e32 v32, v115, v39
	v_fmac_f32_e32 v48, v104, v72
	v_fmac_f32_e32 v32, v104, v40
	v_fmac_f32_e32 v48, v105, v73
	v_fmac_f32_e32 v32, v105, v41
	v_max_f32 v74, 0, v74
	v_max_f32 v42, 0, v42
	v_max_f32 v75, 0, v75
	v_max_f32 v43, 0, v43
	v_max_f32 v76, 0, v76
	v_max_f32 v44, 0, v44
	s_nop 0
	v_fmac_f32_e32 v48, v106, v74
	v_fmac_f32_e32 v32, v106, v42
	v_fmac_f32_e32 v48, v107, v75
	v_fmac_f32_e32 v32, v107, v43
	v_fmac_f32_e32 v48, v96, v76
	v_fmac_f32_e32 v32, v96, v44
	v_max_f32 v77, 0, v77
	v_max_f32 v45, 0, v45
	v_max_f32 v78, 0, v78
	v_max_f32 v46, 0, v46
	v_max_f32 v79, 0, v79
	v_max_f32 v47, 0, v47
	s_nop 0
	v_fmac_f32_e32 v48, v97, v77
	v_fmac_f32_e32 v32, v97, v45
	v_fmac_f32_e32 v48, v98, v78
	v_fmac_f32_e32 v32, v98, v46
	v_fmac_f32_e32 v48, v99, v79
	v_fmac_f32_e32 v32, v99, v47
	s_nop 1
	v_permlane32_swap_b32_e32 v48, v32
	v_add_f32_e32 v32, v48, v32
	s_cmp_lt_u32 s92, 16
	s_cbranch_scc0 .Lidxt2_16_32
	s_cmp_lt_u32 s92, 8
	s_cbranch_scc0 .Lidxt2_8_16
	s_cmp_lt_u32 s92, 4
	s_cbranch_scc0 .Lidxt2_4_8
	s_cmp_lt_u32 s92, 2
	s_cbranch_scc0 .Lidxt2_2_4
	s_cmp_lt_u32 s92, 1
	s_cbranch_scc0 .Lidxt2_1_2
	v_mov_b32_e32 v17, v32
	s_branch .Lidxt2_join

.Lidx_mfma_go:
	s_setprio 1
	s_waitcnt lgkmcnt(11)
	v_mfma_f32_32x32x16_f16 v[48:63], v[128:131], v[32:35], 0
	v_mfma_f32_32x32x16_f16 v[32:47], v[136:139], v[32:35], 0
	s_waitcnt lgkmcnt(10)
	v_mfma_f32_32x32x16_f16 v[48:63], v[132:135], v[64:67], v[48:63]
	v_mfma_f32_32x32x16_f16 v[32:47], v[140:143], v[64:67], v[32:47]
	s_waitcnt lgkmcnt(9)
	v_mfma_f32_32x32x16_f16 v[48:63], v[144:147], v[68:71], v[48:63]
	v_mfma_f32_32x32x16_f16 v[32:47], v[152:155], v[68:71], v[32:47]
	s_waitcnt lgkmcnt(8)
	v_mfma_f32_32x32x16_f16 v[48:63], v[148:151], v[72:75], v[48:63]
	v_mfma_f32_32x32x16_f16 v[32:47], v[156:159], v[72:75], v[32:47]
	s_waitcnt lgkmcnt(6)
	v_mfma_f32_32x32x16_f16 v[48:63], v[160:163], v[76:79], v[48:63]
	v_mfma_f32_32x32x16_f16 v[32:47], v[168:171], v[76:79], v[32:47]
	s_waitcnt lgkmcnt(4)
	v_mfma_f32_32x32x16_f16 v[48:63], v[164:167], v[80:83], v[48:63]
	v_mfma_f32_32x32x16_f16 v[32:47], v[172:175], v[80:83], v[32:47]
	s_waitcnt lgkmcnt(2)
	v_mfma_f32_32x32x16_f16 v[48:63], v[176:179], v[84:87], v[48:63]
	v_mfma_f32_32x32x16_f16 v[32:47], v[184:187], v[84:87], v[32:47]
	s_waitcnt lgkmcnt(0)
	v_mfma_f32_32x32x16_f16 v[48:63], v[180:183], v[88:91], v[48:63]
	v_mfma_f32_32x32x16_f16 v[32:47], v[188:191], v[88:91], v[32:47]
	v_mfma_f32_32x32x16_f16 v[80:95], v[128:131], v[204:207], 0
	v_mfma_f32_32x32x16_f16 v[64:79], v[136:139], v[204:207], 0
	v_mfma_f32_32x32x16_f16 v[80:95], v[132:135], v[196:199], v[80:95]
	v_mfma_f32_32x32x16_f16 v[64:79], v[140:143], v[196:199], v[64:79]
	v_mfma_f32_32x32x16_f16 v[80:95], v[144:147], v[200:203], v[80:95]
	v_mfma_f32_32x32x16_f16 v[64:79], v[152:155], v[200:203], v[64:79]
	v_mfma_f32_32x32x16_f16 v[80:95], v[148:151], v[192:195], v[80:95]
	v_mfma_f32_32x32x16_f16 v[64:79], v[156:159], v[192:195], v[64:79]
	v_mfma_f32_32x32x16_f16 v[80:95], v[160:163], v[236:239], v[80:95]
	v_mfma_f32_32x32x16_f16 v[64:79], v[168:171], v[236:239], v[64:79]
	v_mfma_f32_32x32x16_f16 v[80:95], v[164:167], v[240:243], v[80:95]
	v_mfma_f32_32x32x16_f16 v[64:79], v[172:175], v[240:243], v[64:79]
	v_mfma_f32_32x32x16_f16 v[80:95], v[176:179], v[244:247], v[80:95]
	v_mfma_f32_32x32x16_f16 v[64:79], v[184:187], v[244:247], v[64:79]
	v_mfma_f32_32x32x16_f16 v[80:95], v[180:183], v[248:251], v[80:95]
	v_mfma_f32_32x32x16_f16 v[64:79], v[188:191], v[248:251], v[64:79]
	s_setprio 0
	s_andn2_b64 vcc, exec, s[86:87]
	s_cbranch_vccz .LBB0_1163
	s_mov_b32 s92, s96
	s_branch .LBB0_1164
.Lidx_y_stub:
	s_mov_b32 s32, 0
	s_waitcnt lgkmcnt(0)
	s_branch .Lidx_mfma_go
.LBB0_1179:
	s_mov_b32 s32, 0
	s_cmp_gt_i32 s92, -1
	s_cselect_b64 s[0:1], -1, 0
	s_and_b64 s[0:1], s[84:85], s[0:1]
	s_andn2_b64 vcc, exec, s[0:1]
	s_cbranch_vccnz .LBB0_1181
	v_max_f32 v128, 0, v80
	v_max_f32 v129, 0, v81
	v_fma_f32 v128, v124, v128, 0
	v_fmac_f32_e32 v128, v125, v129
	v_max_f32 v129, 0, v48
	v_fma_f32 v124, v124, v129, 0
	v_max_f32 v129, 0, v49
	v_fmac_f32_e32 v124, v125, v129
	v_max_f32 v125, 0, v82
	v_fmac_f32_e32 v128, v126, v125
	v_max_f32 v125, 0, v50
	v_fmac_f32_e32 v124, v126, v125
	v_max_f32 v125, 0, v83
	v_max_f32 v126, 0, v65
	v_fmac_f32_e32 v128, v127, v125
	v_max_f32 v125, 0, v51
	v_fmac_f32_e32 v124, v127, v125
	v_max_f32 v125, 0, v64
	v_fma_f32 v125, v120, v125, 0
	v_fmac_f32_e32 v125, v121, v126
	v_max_f32 v126, 0, v32
	v_fma_f32 v120, v120, v126, 0
	v_max_f32 v126, 0, v33
	v_fmac_f32_e32 v120, v121, v126
	v_max_f32 v121, 0, v66
	v_fmac_f32_e32 v125, v122, v121
	v_max_f32 v121, 0, v34
	v_fmac_f32_e32 v120, v122, v121
	v_max_f32 v121, 0, v67
	v_fmac_f32_e32 v125, v123, v121
	v_max_f32 v121, 0, v35
	v_fmac_f32_e32 v120, v123, v121
	v_max_f32 v121, 0, v84
	v_fmac_f32_e32 v128, v116, v121
	v_max_f32 v121, 0, v52
	v_fmac_f32_e32 v124, v116, v121
	v_max_f32 v116, 0, v85
	v_fmac_f32_e32 v128, v117, v116
	v_max_f32 v116, 0, v53
	v_fmac_f32_e32 v124, v117, v116
	v_max_f32 v116, 0, v86
	v_fmac_f32_e32 v128, v118, v116
	v_max_f32 v116, 0, v54
	v_fmac_f32_e32 v124, v118, v116
	v_max_f32 v116, 0, v87
	v_fmac_f32_e32 v128, v119, v116
	v_max_f32 v116, 0, v55
	v_fmac_f32_e32 v124, v119, v116
	v_max_f32 v116, 0, v68
	v_fmac_f32_e32 v125, v112, v116
	v_max_f32 v116, 0, v36
	v_fmac_f32_e32 v120, v112, v116
	v_max_f32 v112, 0, v69
	v_fmac_f32_e32 v125, v113, v112
	v_max_f32 v112, 0, v37
	v_fmac_f32_e32 v120, v113, v112
	v_max_f32 v112, 0, v70
	v_fmac_f32_e32 v125, v114, v112
	v_max_f32 v112, 0, v38
	v_fmac_f32_e32 v120, v114, v112
	v_max_f32 v112, 0, v71
	v_fmac_f32_e32 v125, v115, v112
	v_max_f32 v112, 0, v39
	v_fmac_f32_e32 v120, v115, v112
	v_max_f32 v112, 0, v88
	v_fmac_f32_e32 v128, v108, v112
	v_max_f32 v112, 0, v56
	s_nop 0
	v_fmac_f32_e32 v124, v108, v112
	v_max_f32 v108, 0, v89
	s_nop 0
	v_fmac_f32_e32 v128, v109, v108
	v_max_f32 v108, 0, v57
	s_nop 0
	v_fmac_f32_e32 v124, v109, v108
	v_max_f32 v108, 0, v90
	s_nop 0
	v_fmac_f32_e32 v128, v110, v108
	v_max_f32 v108, 0, v58
	s_nop 0
	v_fmac_f32_e32 v124, v110, v108
	v_max_f32 v108, 0, v91
	s_nop 0
	v_fmac_f32_e32 v128, v111, v108
	v_max_f32 v108, 0, v59
	s_nop 0
	v_fmac_f32_e32 v124, v111, v108
	v_max_f32 v108, 0, v72
	s_nop 0
	v_fmac_f32_e32 v125, v104, v108
	v_max_f32 v108, 0, v40
	s_nop 0
	v_fmac_f32_e32 v120, v104, v108
	v_max_f32 v104, 0, v73
	s_nop 0
	v_fmac_f32_e32 v125, v105, v104
	v_max_f32 v104, 0, v41
	s_nop 0
	v_fmac_f32_e32 v120, v105, v104
	v_max_f32 v104, 0, v74
	s_nop 0
	v_fmac_f32_e32 v125, v106, v104
	v_max_f32 v104, 0, v42
	s_nop 0
	v_fmac_f32_e32 v120, v106, v104
	v_max_f32 v104, 0, v75
	s_nop 0
	v_fmac_f32_e32 v125, v107, v104
	v_max_f32 v104, 0, v43
	s_nop 0
	v_fmac_f32_e32 v120, v107, v104
	v_max_f32 v104, 0, v92
	s_nop 0
	v_fmac_f32_e32 v128, v100, v104
	v_max_f32 v104, 0, v60
	s_nop 0
	v_fmac_f32_e32 v124, v100, v104
	v_max_f32 v100, 0, v93
	s_nop 0
	v_fmac_f32_e32 v128, v101, v100
	v_max_f32 v100, 0, v61
	s_nop 0
	v_fmac_f32_e32 v124, v101, v100
	v_max_f32 v100, 0, v94
	s_nop 0
	v_fmac_f32_e32 v128, v102, v100
	v_max_f32 v100, 0, v62
	s_nop 0
	v_fmac_f32_e32 v124, v102, v100
	v_max_f32 v100, 0, v95
	s_nop 0
	v_fmac_f32_e32 v128, v103, v100
	v_max_f32 v100, 0, v63
	s_nop 0
	v_fmac_f32_e32 v124, v103, v100
	v_max_f32 v100, 0, v76
	s_nop 1
	v_permlane32_swap_b32_e32 v128, v124
	v_fmac_f32_e32 v125, v96, v100
	v_max_f32 v100, 0, v44
	s_nop 0
	v_fmac_f32_e32 v120, v96, v100
	v_max_f32 v96, 0, v77
	s_nop 0
	v_fmac_f32_e32 v125, v97, v96
	v_max_f32 v96, 0, v45
	s_nop 0
	v_fmac_f32_e32 v120, v97, v96
	v_max_f32 v96, 0, v78
	v_lshl_add_u32 v97, s92, 8, v224
	v_fmac_f32_e32 v125, v98, v96
	v_max_f32 v96, 0, v46
	s_nop 0
	v_fmac_f32_e32 v120, v98, v96
	v_max_f32 v96, 0, v79
	s_nop 0
	v_fmac_f32_e32 v125, v99, v96
	v_max_f32 v96, 0, v47
	s_nop 0
	v_fmac_f32_e32 v120, v99, v96
	v_add_f32_e32 v96, v128, v124
	s_nop 0
	v_permlane32_swap_b32_e32 v125, v120
	ds_write_b32 v97, v96
	v_add_f32_e32 v96, v125, v120
	s_cmp_lt_u32 s92, 16
	s_cbranch_scc0 .Lidxt3_16_32
	s_cmp_lt_u32 s92, 8
	s_cbranch_scc0 .Lidxt3_8_16
	s_cmp_lt_u32 s92, 4
	s_cbranch_scc0 .Lidxt3_4_8
	s_cmp_lt_u32 s92, 2
	s_cbranch_scc0 .Lidxt3_2_4
	s_cmp_lt_u32 s92, 1
	s_cbranch_scc0 .Lidxt3_1_2
	v_mov_b32_e32 v17, v96
	s_branch .Lidxt3_join
